# GDN seq scan: loop-invariant norm weights hoisted out of step loop, counted vmcnt keeps next-step operand prefetch in flight
# baseline (speedup 1.0000x reference)
; #define LAS __attribute__((address_space(3)))
; DI f32x4 mfma16(bf16x8 a, bf16x8 b, f32x4 c) { return __builtin_amdgcn_mfma_f32_16x16x32_bf16(a, b, c, 0, 0, 0); }
; DI void gdn_seq_phase(const int tid, LAS unsigned char* lds, const P& p, int G, int c) {
;     ...
;     for (int u = c; u < 192; u += G) {
;         const int h = u % 6, b = u / 6;
;         for (int i = tid; i < 128 * 136 / 2; i += 512) ((LAS unsigned*)ST)[i] = 0u;
;         f32x4 Sacc[8];
; #pragma unroll
;         for (int e = 0; e < 8; ++e) Sacc[e] = (f32x4){0.f, 0.f, 0.f, 0.f};
;         __syncthreads();
;         bf16x8 Wf[4], Qf[4], If[2], Kf[2]; u32x2 uvr[4]; float gl;
;         const int wrow = (ct * 16 + fr) * 128 + fq * 8, irow = (ct * 16 + fr) * 64 + fq * 8, krow = (w * 16 + fr) * 64 + fq * 8;
;         { const size_t cid = (size_t)u * 32;
; #pragma unroll
;           for (int ks = 0; ks < 4; ++ks) { Wf[ks] = *(const bf16x8*)(Wc + cid * 8192 + wrow + ks * 32); Qf[ks] = *(const bf16x8*)(QDc + cid * 8192 + wrow + ks * 32); }
; #pragma unroll
;           for (int ks = 0; ks < 2; ++ks) { If[ks] = *(const bf16x8*)(INc + cid * 4096 + irow + ks * 32); Kf[ks] = *(const bf16x8*)(KDTc + cid * 8192 + krow + ks * 32); }
; #pragma unroll
;           for (int et = 0; et < 4; ++et) uvr[et] = *(const u32x2*)(Uc + cid * 8192 + (eh * 64 + et * 16 + fr) * 64 + ct * 16 + fq * 4);
;           gl = GLc[cid]; }
;         for (int n = 0; n < 32; ++n) {
;             const size_t cid = (size_t)u * 32 + n, cnx = (cid + 1 < 6144) ? cid + 1 : cid;
;             const int tt = tid >> 3, e0 = (tid & 7) * 16; const size_t tok = (size_t)b * SEQ + n * 64 + tt;
;             const u32x4 z0 = *(const u32x4*)(Z + tok * 768 + h * 128 + e0), z1 = *(const u32x4*)(Z + tok * 768 + h * 128 + e0 + 8);
;             f32x4 T1[4], O1[4];
; #pragma unroll
;             for (int et = 0; et < 4; ++et) { T1[et] = (f32x4){0.f, 0.f, 0.f, 0.f}; O1[et] = (f32x4){0.f, 0.f, 0.f, 0.f};
; #pragma unroll
;                 for (int ks = 0; ks < 4; ++ks) { const bf16x8 bb = *(const LAS bf16x8*)(ST + (eh * 64 + et * 16 + fr) * 136 + ks * 32 + fq * 8); T1[et] = mfma16(Wf[ks], bb, T1[et]); O1[et] = mfma16(Qf[ks], bb, O1[et]); } }
.LBB0_563:
	s_or_b64 exec, exec, s[0:1]
	s_ashr_i32 s9, s8, 31
	s_lshl_b64 s[12:13], s[8:9], 19
	s_mul_hi_i32 s0, s8, 0x2aaaaaab
	v_lshl_add_u64 v[0:1], v[124:125], 0, s[12:13]
	s_lshr_b32 s1, s0, 31
	s_waitcnt lgkmcnt(0)
	s_barrier
	v_lshl_add_u64 v[2:3], v[126:127], 0, s[12:13]
	global_load_dwordx4 v[184:187], v[122:123], off offset:48
	global_load_dwordx4 v[188:191], v[122:123], off offset:32
	global_load_dwordx4 v[192:195], v[122:123], off offset:16
	global_load_dwordx4 v[196:199], v[122:123], off
	global_load_dwordx4 v[44:47], v[0:1], off
	global_load_dwordx4 v[36:39], v[0:1], off offset:64
	global_load_dwordx4 v[48:51], v[2:3], off
	global_load_dwordx4 v[40:43], v[2:3], off offset:64
	global_load_dwordx4 v[24:27], v[0:1], off offset:128
	global_load_dwordx4 v[16:19], v[0:1], off offset:192
	global_load_dwordx4 v[28:31], v[2:3], off offset:128
	global_load_dwordx4 v[20:23], v[2:3], off offset:192
	s_add_i32 s0, s0, s1
	s_mul_i32 s1, s0, 6
	s_lshl_b64 s[10:11], s[8:9], 18
	v_lshl_add_u64 v[32:33], v[132:133], 0, s[12:13]
	s_sub_i32 s14, s8, s1
	v_lshl_add_u64 v[0:1], v[128:129], 0, s[10:11]
	v_lshl_add_u64 v[2:3], v[130:131], 0, s[12:13]
	v_lshl_add_u64 v[34:35], v[134:135], 1, v[32:33]
	s_lshl_b64 s[10:11], s[8:9], 7
	v_lshl_add_u64 v[52:53], v[136:137], 1, v[32:33]
	v_lshl_add_u64 v[32:33], v[138:139], 1, v[32:33]
	global_load_dwordx2 v[156:157], v[34:35], off
	global_load_dwordx2 v[154:155], v[34:35], off offset:2048
	global_load_dwordx2 v[152:153], v[52:53], off
	global_load_dwordx2 v[144:145], v[32:33], off
	s_add_u32 s10, s33, s10
	s_addc_u32 s11, s88, s11
	global_load_dword v148, v181, s[10:11]
	global_load_dwordx4 v[8:11], v[0:1], off
	global_load_dwordx4 v[12:15], v[0:1], off offset:64
	global_load_dwordx4 v[4:7], v[2:3], off
	s_nop 0
	global_load_dwordx4 v[0:3], v[2:3], off offset:64
	global_load_dword v173, v181, s[10:11]
	global_load_dword v173, v181, s[10:11]
	s_ashr_i32 s1, s0, 31
	s_lshl_b32 s10, s14, 7
	v_mov_b32_e32 v32, 0x300000
	s_ashr_i32 s11, s10, 31
	s_lshl_b64 s[12:13], s[0:1], 22
	v_mad_i64_i32 v[150:151], s[0:1], s0, v32, v[142:143]
	v_mov_b32_e32 v32, 0
	s_lshl_b64 s[10:11], s[10:11], 1
	v_lshl_add_u64 v[146:147], v[140:141], 0, s[12:13]
	s_mov_b64 s[12:13], 0
	v_mov_b32_e32 v33, v32
	v_mov_b32_e32 v34, v32
	v_mov_b32_e32 v35, v32
	v_mov_b32_e32 v52, v32
	v_mov_b32_e32 v53, v32
	v_mov_b32_e32 v54, v32
	v_mov_b32_e32 v55, v32
	v_mov_b32_e32 v56, v32
	v_mov_b32_e32 v57, v32
	v_mov_b32_e32 v58, v32
	v_mov_b32_e32 v59, v32
	v_mov_b32_e32 v60, v32
	v_mov_b32_e32 v61, v32
	v_mov_b32_e32 v62, v32
	v_mov_b32_e32 v63, v32
	v_mov_b32_e32 v64, v32
	v_mov_b32_e32 v65, v32
	v_mov_b32_e32 v66, v32
	v_mov_b32_e32 v67, v32
	v_mov_b32_e32 v68, v32
	v_mov_b32_e32 v69, v32
	v_mov_b32_e32 v70, v32
	v_mov_b32_e32 v71, v32
	v_mov_b32_e32 v72, v32
	v_mov_b32_e32 v73, v32
	v_mov_b32_e32 v74, v32
	v_mov_b32_e32 v75, v32
	v_mov_b32_e32 v76, v32
	v_mov_b32_e32 v77, v32
	v_mov_b32_e32 v78, v32
	v_mov_b32_e32 v79, v32
.LBB0_564:
	s_add_u32 s9, s6, s12
	s_addc_u32 s16, s7, s13
	s_add_u32 s14, s9, 1
	s_addc_u32 s15, s16, 0
	v_mov_b64_e32 v[80:81], 0x1800
	v_cmp_lt_u64_e32 vcc, s[14:15], v[80:81]
	v_lshl_add_u64 v[80:81], v[150:151], 0, s[10:11]
	s_mov_b64 s[0:1], 0x16000000
	v_lshl_add_u64 v[82:83], v[80:81], 0, s[0:1]
	s_mov_b32 s0, 0x16000000
	v_add_co_u32_e64 v80, s[0:1], s0, v80
	s_waitcnt vmcnt(10)
	v_lshlrev_b32_e32 v171, 16, v156
	v_addc_co_u32_e64 v81, s[0:1], 0, v81, s[0:1]
	global_load_dwordx4 v[84:87], v[80:81], off
	s_nop 0
	global_load_dwordx4 v[80:83], v[82:83], off offset:16
	ds_read_b128 v[88:91], v167
	ds_read_b128 v[96:99], v167 offset:64
	s_waitcnt lgkmcnt(1)
	v_mfma_f32_16x16x32_bf16 v[92:95], v[44:47], v[88:91], 0
	ds_read_b128 v[100:103], v167 offset:4416
	ds_read_b128 v[112:115], v167 offset:8768
	v_and_b32_e32 v156, 0xffff0000, v156
	v_mfma_f32_16x16x32_bf16 v[88:91], v[48:51], v[88:91], 0
	s_and_b64 s[0:1], vcc, exec
	ds_read_b128 v[116:119], v167 offset:8896
	s_cselect_b32 s1, s15, s16
	s_waitcnt lgkmcnt(3)
	v_mfma_f32_16x16x32_bf16 v[92:95], v[36:39], v[96:99], v[92:95]
	s_cselect_b32 s0, s14, s9
	s_lshl_b64 s[14:15], s[0:1], 14
	s_lshl_b64 s[16:17], s[0:1], 13
	v_mfma_f32_16x16x32_bf16 v[88:91], v[40:43], v[96:99], v[88:91]
	ds_read_b128 v[96:99], v167 offset:128
	s_waitcnt vmcnt(8)
	v_pk_mul_f32 v[34:35], v[34:35], v[148:149] op_sel_hi:[1,0]
	v_pk_mul_f32 v[32:33], v[32:33], v[148:149] op_sel_hi:[1,0]
	s_waitcnt lgkmcnt(0)
	v_mfma_f32_16x16x32_bf16 v[92:95], v[24:27], v[96:99], v[92:95]
	v_mul_f32_e64 v54, v54, v148
	v_mul_f32_e64 v55, v55, v148
	v_pk_mul_f32 v[52:53], v[52:53], v[148:149] op_sel_hi:[1,0]
	v_pk_mul_f32 v[58:59], v[58:59], v[148:149] op_sel_hi:[1,0]
	v_mfma_f32_16x16x32_bf16 v[88:91], v[28:31], v[96:99], v[88:91]
	ds_read_b128 v[96:99], v167 offset:192
	v_pk_mul_f32 v[56:57], v[56:57], v[148:149] op_sel_hi:[1,0]
	v_pk_mul_f32 v[62:63], v[62:63], v[148:149] op_sel_hi:[1,0]
	s_waitcnt lgkmcnt(0)
	v_mfma_f32_16x16x32_bf16 v[104:107], v[16:19], v[96:99], v[92:95]
	v_mul_f32_e64 v60, v60, v148
	v_mul_f32_e64 v61, v61, v148
	s_nop 0
	ds_read_b128 v[92:95], v167 offset:4352
	v_pk_mul_f32 v[66:67], v[66:67], v[148:149] op_sel_hi:[1,0]
	v_mfma_f32_16x16x32_bf16 v[88:91], v[20:23], v[96:99], v[88:91]
	s_nop 1
	v_sub_f32_e32 v104, v171, v104
	v_sub_f32_e32 v105, v156, v105
	v_cvt_pk_bf16_f32 v104, v104, v105
	s_waitcnt lgkmcnt(0)
; #define LAS __attribute__((address_space(3)))
; DI float lo16(unsigned u) { return __uint_as_float(u << 16); }
; DI float hi16(unsigned u) { return __uint_as_float(u & 0xffff0000u); }
; DI f32x4 mfma16(bf16x8 a, bf16x8 b, f32x4 c) { return __builtin_amdgcn_mfma_f32_16x16x32_bf16(a, b, c, 0, 0, 0); }
; DI void gdn_seq_phase(const int tid, LAS unsigned char* lds, const P& p, int G, int c) {
;     ...
;             f32x4 T1[4], O1[4];
; #pragma unroll
;             for (int et = 0; et < 4; ++et) { T1[et] = (f32x4){0.f, 0.f, 0.f, 0.f}; O1[et] = (f32x4){0.f, 0.f, 0.f, 0.f};
; #pragma unroll
;                 for (int ks = 0; ks < 4; ++ks) { const bf16x8 bb = *(const LAS bf16x8*)(ST + (eh * 64 + et * 16 + fr) * 136 + ks * 32 + fq * 8); T1[et] = mfma16(Wf[ks], bb, T1[et]); O1[et] = mfma16(Qf[ks], bb, O1[et]); } }
; #pragma unroll
;             for (int ks = 0; ks < 4; ++ks) { Wf[ks] = *(const bf16x8*)(Wc + cnx * 8192 + wrow + ks * 32); Qf[ks] = *(const bf16x8*)(QDc + cnx * 8192 + wrow + ks * 32); }
; #pragma unroll
;             for (int et = 0; et < 4; ++et) { u32x2 pk; pk.x = pk2(lo16(uvr[et].x) - T1[et][0], hi16(uvr[et].x) - T1[et][1]); pk.y = pk2(lo16(uvr[et].y) - T1[et][2], hi16(uvr[et].y) - T1[et][3]);
;                 *(LAS u32x2*)(VT + (eh * 64 + et * 16 + fr) * 72 + ct * 16 + fq * 4) = pk; }
; #pragma unroll
;             for (int et = 0; et < 4; ++et) uvr[et] = *(const u32x2*)(Uc + cnx * 8192 + (eh * 64 + et * 16 + fr) * 64 + ct * 16 + fq * 4);
;     ...
;             gl = GLc[cnx];
	v_mfma_f32_16x16x32_bf16 v[96:99], v[44:47], v[92:95], 0
	v_lshlrev_b32_e32 v105, 16, v157
	v_sub_f32_e32 v105, v105, v106
	v_and_b32_e32 v106, 0xffff0000, v157
	v_mfma_f32_16x16x32_bf16 v[92:95], v[48:51], v[92:95], 0
	v_sub_f32_e32 v106, v106, v107
	v_cvt_pk_bf16_f32 v105, v105, v106
	v_and_b32_e32 v106, 0xffff0000, v155
	v_mfma_f32_16x16x32_bf16 v[96:99], v[36:39], v[100:103], v[96:99]
	v_mul_f32_e64 v64, v64, v148
	v_mul_f32_e64 v65, v65, v148
	v_pk_mul_f32 v[70:71], v[70:71], v[148:149] op_sel_hi:[1,0]
	v_pk_mul_f32 v[68:69], v[68:69], v[148:149] op_sel_hi:[1,0]
	v_mfma_f32_16x16x32_bf16 v[92:95], v[40:43], v[100:103], v[92:95]
	ds_read_b128 v[100:103], v167 offset:4480
	v_pk_mul_f32 v[74:75], v[74:75], v[148:149] op_sel_hi:[1,0]
	v_pk_mul_f32 v[72:73], v[72:73], v[148:149] op_sel_hi:[1,0]
	s_waitcnt lgkmcnt(0)
	v_mfma_f32_16x16x32_bf16 v[96:99], v[24:27], v[100:103], v[96:99]
	v_mul_f32_e64 v78, v78, v148
	v_mul_f32_e64 v79, v79, v148
	v_pk_mul_f32 v[76:77], v[76:77], v[148:149] op_sel_hi:[1,0]
	s_lshl_b64 s[0:1], s[0:1], 2
	v_mfma_f32_16x16x32_bf16 v[92:95], v[28:31], v[100:103], v[92:95]
	ds_read_b128 v[100:103], v167 offset:4544
	s_add_u32 s0, s33, s0
	s_addc_u32 s1, s88, s1
	s_waitcnt lgkmcnt(0)
	v_mfma_f32_16x16x32_bf16 v[108:111], v[16:19], v[100:103], v[96:99]
	s_add_u32 s12, s12, 1
	s_nop 1
	ds_read_b128 v[96:99], v167 offset:8704
	s_addc_u32 s13, s13, 0
	v_mfma_f32_16x16x32_bf16 v[92:95], v[20:23], v[100:103], v[92:95]
	s_nop 1
	v_sub_f32_e32 v106, v106, v111
	s_cmp_eq_u32 s12, 32
	s_waitcnt vmcnt(1)
	v_lshlrev_b32_e32 v174, 16, v84
	s_waitcnt lgkmcnt(0)
	v_mfma_f32_16x16x32_bf16 v[100:103], v[44:47], v[96:99], 0
	v_and_b32_e32 v175, 0xffff0000, v84
	v_mul_f32_e32 v84, 0xbfb8aa3b, v174
	v_exp_f32_e32 v84, v84
	v_mfma_f32_16x16x32_bf16 v[96:99], v[48:51], v[96:99], 0
	v_add_f32_e32 v84, 1.0, v84
	v_mfma_f32_16x16x32_bf16 v[100:103], v[36:39], v[112:115], v[100:103]
	v_rcp_f32_e32 v176, v84
	v_mul_f32_e32 v84, 0xbfb8aa3b, v175
	v_exp_f32_e32 v84, v84
	v_mfma_f32_16x16x32_bf16 v[96:99], v[40:43], v[112:115], v[96:99]
	ds_read_b128 v[112:115], v167 offset:8832
	v_add_f32_e32 v84, 1.0, v84
	s_waitcnt lgkmcnt(0)
	v_mfma_f32_16x16x32_bf16 v[100:103], v[24:27], v[112:115], v[100:103]
	v_rcp_f32_e32 v177, v84
	v_mfma_f32_16x16x32_bf16 v[96:99], v[28:31], v[112:115], v[96:99]
	v_mfma_f32_16x16x32_bf16 v[112:115], v[16:19], v[116:119], v[100:103]
	s_nop 4
	ds_read_b128 v[100:103], v167 offset:13056
	s_waitcnt lgkmcnt(0)
	v_mfma_f32_16x16x32_bf16 v[44:47], v[44:47], v[100:103], 0
	v_mfma_f32_16x16x32_bf16 v[48:51], v[48:51], v[100:103], 0
	ds_read_b128 v[100:103], v167 offset:13120
	s_waitcnt lgkmcnt(0)
	v_mfma_f32_16x16x32_bf16 v[36:39], v[36:39], v[100:103], v[44:47]
	s_nop 3
	ds_read_b128 v[44:47], v167 offset:13184
	v_mfma_f32_16x16x32_bf16 v[40:43], v[40:43], v[100:103], v[48:51]
	s_waitcnt lgkmcnt(0)
	v_mfma_f32_16x16x32_bf16 v[24:27], v[24:27], v[44:47], v[36:39]
	s_nop 2
	ds_read_b128 v[36:39], v167 offset:13248
	v_mfma_f32_16x16x32_bf16 v[28:31], v[28:31], v[44:47], v[40:43]
	v_mfma_f32_16x16x32_bf16 v[96:99], v[20:23], v[116:119], v[96:99]
	s_waitcnt lgkmcnt(0)
	v_mfma_f32_16x16x32_bf16 v[116:119], v[16:19], v[36:39], v[24:27]
	v_lshl_add_u64 v[16:17], v[124:125], 0, s[14:15]
	v_mfma_f32_16x16x32_bf16 v[100:103], v[20:23], v[36:39], v[28:31]
	v_lshl_add_u64 v[20:21], v[126:127], 0, s[14:15]
	global_load_dwordx4 v[44:47], v[16:17], off
	global_load_dwordx4 v[48:51], v[20:21], off
	global_load_dwordx4 v[36:39], v[16:17], off offset:64
	global_load_dwordx4 v[40:43], v[20:21], off offset:64
	global_load_dwordx4 v[24:27], v[16:17], off offset:128
	global_load_dwordx4 v[28:31], v[20:21], off offset:128
	s_nop 0
	global_load_dwordx4 v[16:19], v[16:17], off offset:192
	s_nop 0
	global_load_dwordx4 v[20:23], v[20:21], off offset:192
	ds_write_b64 v168, v[104:105] offset:34816
	v_lshlrev_b32_e32 v104, 16, v154
	v_and_b32_e32 v105, 0xffff0000, v154
	v_sub_f32_e32 v104, v104, v108
	v_sub_f32_e32 v105, v105, v109
	v_cvt_pk_bf16_f32 v104, v104, v105
	v_lshlrev_b32_e32 v105, 16, v155
	v_sub_f32_e32 v105, v105, v110
	v_cvt_pk_bf16_f32 v105, v105, v106
	ds_write_b64 v168, v[104:105] offset:37120
	v_lshlrev_b32_e32 v104, 16, v152
	v_and_b32_e32 v105, 0xffff0000, v152
	v_sub_f32_e32 v104, v104, v112
	v_sub_f32_e32 v105, v105, v113
	v_cvt_pk_bf16_f32 v104, v104, v105
	v_lshlrev_b32_e32 v105, 16, v153
	v_and_b32_e32 v106, 0xffff0000, v153
	v_sub_f32_e32 v105, v105, v114
	v_sub_f32_e32 v106, v106, v115
	v_cvt_pk_bf16_f32 v105, v105, v106
	ds_write_b64 v168, v[104:105] offset:39424
	v_lshlrev_b32_e32 v104, 16, v144
	v_and_b32_e32 v105, 0xffff0000, v144
	v_sub_f32_e32 v104, v104, v116
	v_sub_f32_e32 v105, v105, v117
	v_cvt_pk_bf16_f32 v104, v104, v105
	v_lshlrev_b32_e32 v105, 16, v145
	v_and_b32_e32 v106, 0xffff0000, v145
	v_sub_f32_e32 v105, v105, v118
	v_sub_f32_e32 v106, v106, v119
	v_cvt_pk_bf16_f32 v105, v105, v106
	ds_write_b64 v168, v[104:105] offset:41728
	v_lshl_add_u64 v[104:105], v[132:133], 0, s[14:15]
	v_lshl_add_u64 v[106:107], v[134:135], 1, v[104:105]
	global_load_dwordx2 v[156:157], v[106:107], off
	global_load_dwordx2 v[154:155], v[106:107], off offset:2048
	v_lshl_add_u64 v[106:107], v[136:137], 1, v[104:105]
	v_lshl_add_u64 v[104:105], v[138:139], 1, v[104:105]
	v_add_u32_e32 v108, v121, v163
	global_load_dwordx2 v[152:153], v[106:107], off
	global_load_dwordx2 v[144:145], v[104:105], off
	global_load_dword v148, v181, s[0:1]
	s_waitcnt lgkmcnt(0)
	s_barrier
; #define LAS __attribute__((address_space(3)))
; DI f32x4 mfma16(bf16x8 a, bf16x8 b, f32x4 c) { return __builtin_amdgcn_mfma_f32_16x16x32_bf16(a, b, c, 0, 0, 0); }
; DI void gdn_seq_phase(const int tid, LAS unsigned char* lds, const P& p, int G, int c) {
;     ...
;             __syncthreads();
; #pragma unroll
;             for (int et = 0; et < 4; ++et) {
; #pragma unroll
;                 for (int ks = 0; ks < 2; ++ks) { const bf16x8 bb = *(const LAS bf16x8*)(VT + (eh * 64 + et * 16 + fr) * 72 + ks * 32 + fq * 8); O1[et] = mfma16(If[ks], bb, O1[et]); }
; #pragma unroll
;                 for (int j = 0; j < 4; ++j) OT[(ct * 16 + fq * 4 + j) * 132 + eh * 64 + et * 16 + fr] = O1[et][j]; }
; #pragma unroll
;             for (int ks = 0; ks < 2; ++ks) If[ks] = *(const bf16x8*)(INc + cnx * 4096 + irow + ks * 32);
; #pragma unroll
;             for (int e8 = 0; e8 < 8; ++e8) { Sacc[e8] = Sacc[e8] * gl;
; #pragma unroll
;                 for (int ks = 0; ks < 2; ++ks) { const bf16x8 aa = *(const LAS bf16x8*)(VT + (e8 * 16 + fr) * 72 + ks * 32 + fq * 8); Sacc[e8] = mfma16(aa, Kf[ks], Sacc[e8]); } }
; #pragma unroll
;             for (int ks = 0; ks < 2; ++ks) Kf[ks] = *(const bf16x8*)(KDTc + cnx * 8192 + krow + ks * 32);
;             gl = GLc[cnx];
; #pragma unroll
;             for (int e8 = 0; e8 < 8; ++e8)
; #pragma unroll
;                 for (int j = 0; j < 4; ++j) ST[(e8 * 16 + fq * 4 + j) * 136 + w * 16 + fr] = f2bf(Sacc[e8][j]);
;             __syncthreads();
	ds_read_b128 v[104:107], v108 offset:34816
	s_waitcnt lgkmcnt(0)
	v_mfma_f32_16x16x32_bf16 v[88:91], v[8:11], v[104:107], v[88:91]
	ds_read_b128 v[104:107], v108 offset:34880
	s_waitcnt lgkmcnt(0)
	v_mfma_f32_16x16x32_bf16 v[88:91], v[12:15], v[104:107], v[88:91]
	s_nop 7
	ds_write_b32 v169, v88 offset:53248
	ds_write_b32 v169, v89 offset:53776
	ds_write_b32 v169, v90 offset:54304
	ds_write_b32 v169, v91 offset:54832
	ds_read_b128 v[88:91], v108 offset:37120
	s_waitcnt lgkmcnt(0)
	v_mfma_f32_16x16x32_bf16 v[88:91], v[8:11], v[88:91], v[92:95]
	s_nop 2
	ds_read_b128 v[92:95], v108 offset:37184
	s_waitcnt lgkmcnt(0)
	v_mfma_f32_16x16x32_bf16 v[88:91], v[12:15], v[92:95], v[88:91]
	s_nop 7
	ds_write_b32 v169, v88 offset:53312
	ds_write_b32 v169, v89 offset:53840
	ds_write_b32 v169, v90 offset:54368
	ds_write_b32 v169, v91 offset:54896
	ds_read_b128 v[88:91], v108 offset:39424
	ds_read_b128 v[92:95], v108 offset:39488
	s_waitcnt lgkmcnt(1)
	v_mfma_f32_16x16x32_bf16 v[88:91], v[8:11], v[88:91], v[96:99]
	s_waitcnt lgkmcnt(0)
	v_mfma_f32_16x16x32_bf16 v[88:91], v[12:15], v[92:95], v[88:91]
	s_nop 7
	ds_write_b32 v169, v88 offset:53376
	ds_write_b32 v169, v89 offset:53904
	ds_write_b32 v169, v90 offset:54432
	ds_write_b32 v169, v91 offset:54960
	ds_read_b128 v[88:91], v108 offset:41728
	s_waitcnt lgkmcnt(0)
	v_mfma_f32_16x16x32_bf16 v[8:11], v[8:11], v[88:91], v[100:103]
	ds_read_b128 v[88:91], v108 offset:41792
	s_waitcnt lgkmcnt(0)
	v_mfma_f32_16x16x32_bf16 v[8:11], v[12:15], v[88:91], v[8:11]
	s_nop 7
	ds_write_b32 v169, v8 offset:53440
	ds_write_b32 v169, v9 offset:53968
	ds_write_b32 v169, v10 offset:54496
	ds_write_b32 v169, v11 offset:55024
	v_lshl_add_u64 v[12:13], v[128:129], 0, s[16:17]
	global_load_dwordx4 v[8:11], v[12:13], off
	s_nop 0
	global_load_dwordx4 v[12:15], v[12:13], off offset:64
	ds_read_b128 v[88:91], v170 offset:34816
	s_waitcnt lgkmcnt(0)
	v_mfma_f32_16x16x32_bf16 v[32:35], v[88:91], v[4:7], v[32:35]
	ds_read_b128 v[88:91], v170 offset:34880
	s_waitcnt lgkmcnt(0)
	v_mfma_f32_16x16x32_bf16 v[32:35], v[88:91], v[0:3], v[32:35]
	ds_read_b128 v[88:91], v170 offset:37120
	s_waitcnt lgkmcnt(0)
	v_mfma_f32_16x16x32_bf16 v[52:55], v[88:91], v[4:7], v[52:55]
	ds_read_b128 v[88:91], v170 offset:37184
	s_waitcnt lgkmcnt(0)
	v_mfma_f32_16x16x32_bf16 v[52:55], v[88:91], v[0:3], v[52:55]
	ds_read_b128 v[88:91], v170 offset:39424
	s_waitcnt lgkmcnt(0)
	v_mfma_f32_16x16x32_bf16 v[56:59], v[88:91], v[4:7], v[56:59]
	ds_read_b128 v[88:91], v170 offset:39488
	s_waitcnt lgkmcnt(0)
	v_mfma_f32_16x16x32_bf16 v[56:59], v[88:91], v[0:3], v[56:59]
	ds_read_b128 v[88:91], v170 offset:41728
	s_waitcnt lgkmcnt(0)
	v_mfma_f32_16x16x32_bf16 v[60:63], v[88:91], v[4:7], v[60:63]
	ds_read_b128 v[88:91], v170 offset:41792
	s_waitcnt lgkmcnt(0)
	v_mfma_f32_16x16x32_bf16 v[60:63], v[88:91], v[0:3], v[60:63]
	ds_read_b128 v[88:91], v170 offset:44032
	s_waitcnt lgkmcnt(0)
	v_mfma_f32_16x16x32_bf16 v[64:67], v[88:91], v[4:7], v[64:67]
	ds_read_b128 v[88:91], v170 offset:44096
	s_waitcnt lgkmcnt(0)
	v_mfma_f32_16x16x32_bf16 v[64:67], v[88:91], v[0:3], v[64:67]
	ds_read_b128 v[88:91], v170 offset:46336
	s_waitcnt lgkmcnt(0)
	v_mfma_f32_16x16x32_bf16 v[68:71], v[88:91], v[4:7], v[68:71]
	ds_read_b128 v[88:91], v170 offset:46400
	s_waitcnt lgkmcnt(0)
	v_mfma_f32_16x16x32_bf16 v[68:71], v[88:91], v[0:3], v[68:71]
	ds_read_b128 v[88:91], v170 offset:48640
	s_waitcnt lgkmcnt(0)
	v_mfma_f32_16x16x32_bf16 v[72:75], v[88:91], v[4:7], v[72:75]
	ds_read_b128 v[88:91], v170 offset:48704
	s_waitcnt lgkmcnt(0)
	v_mfma_f32_16x16x32_bf16 v[72:75], v[88:91], v[0:3], v[72:75]
	ds_read_b128 v[88:91], v170 offset:50944
	s_waitcnt lgkmcnt(0)
	v_mfma_f32_16x16x32_bf16 v[4:7], v[88:91], v[4:7], v[76:79]
	s_nop 2
	ds_read_b128 v[76:79], v170 offset:51008
	v_cvt_pk_bf16_f32 v88, v32, s0
	s_waitcnt lgkmcnt(0)
	v_mfma_f32_16x16x32_bf16 v[76:79], v[76:79], v[0:3], v[4:7]
	v_lshl_add_u64 v[0:1], v[130:131], 0, s[14:15]
	s_nop 1
	global_load_dwordx4 v[4:7], v[0:1], off
	s_nop 0
	global_load_dwordx4 v[0:3], v[0:1], off offset:64
	ds_write_b16 v164, v88
	v_cvt_pk_bf16_f32 v88, v33, s0
	ds_write_b16 v164, v88 offset:272
	v_cvt_pk_bf16_f32 v88, v34, s0
	ds_write_b16 v164, v88 offset:544
	v_cvt_pk_bf16_f32 v88, v35, s0
	ds_write_b16 v164, v88 offset:816
	v_cvt_pk_bf16_f32 v88, v52, s0
	ds_write_b16 v164, v88 offset:4352
	v_cvt_pk_bf16_f32 v88, v53, s0
	ds_write_b16 v164, v88 offset:4624
	v_cvt_pk_bf16_f32 v88, v54, s0
	ds_write_b16 v164, v88 offset:4896
	v_cvt_pk_bf16_f32 v88, v55, s0
	ds_write_b16 v164, v88 offset:5168
	v_cvt_pk_bf16_f32 v88, v56, s0
	ds_write_b16 v164, v88 offset:8704
	v_cvt_pk_bf16_f32 v88, v57, s0
	ds_write_b16 v164, v88 offset:8976
	v_cvt_pk_bf16_f32 v88, v58, s0
	ds_write_b16 v164, v88 offset:9248
	v_cvt_pk_bf16_f32 v88, v59, s0
	ds_write_b16 v164, v88 offset:9520
	v_cvt_pk_bf16_f32 v88, v60, s0
	ds_write_b16 v164, v88 offset:13056
	v_cvt_pk_bf16_f32 v88, v61, s0
	ds_write_b16 v164, v88 offset:13328
	v_cvt_pk_bf16_f32 v88, v62, s0
	ds_write_b16 v164, v88 offset:13600
	v_cvt_pk_bf16_f32 v88, v63, s0
	ds_write_b16 v164, v88 offset:13872
	v_cvt_pk_bf16_f32 v88, v64, s0
	ds_write_b16 v164, v88 offset:17408
	v_cvt_pk_bf16_f32 v88, v65, s0
	ds_write_b16 v164, v88 offset:17680
	v_cvt_pk_bf16_f32 v88, v66, s0
	ds_write_b16 v164, v88 offset:17952
	v_cvt_pk_bf16_f32 v88, v67, s0
	ds_write_b16 v164, v88 offset:18224
	v_cvt_pk_bf16_f32 v88, v68, s0
	ds_write_b16 v164, v88 offset:21760
	v_cvt_pk_bf16_f32 v88, v69, s0
	ds_write_b16 v164, v88 offset:22032
	v_cvt_pk_bf16_f32 v88, v70, s0
	ds_write_b16 v164, v88 offset:22304
	v_cvt_pk_bf16_f32 v88, v71, s0
	ds_write_b16 v164, v88 offset:22576
	v_cvt_pk_bf16_f32 v88, v72, s0
	ds_write_b16 v164, v88 offset:26112
	v_cvt_pk_bf16_f32 v88, v73, s0
	ds_write_b16 v164, v88 offset:26384
	v_cvt_pk_bf16_f32 v88, v74, s0
	ds_write_b16 v164, v88 offset:26656
	v_cvt_pk_bf16_f32 v88, v75, s0
	ds_write_b16 v164, v88 offset:26928
	v_cvt_pk_bf16_f32 v88, v76, s0
	ds_write_b16 v164, v88 offset:30464
	v_cvt_pk_bf16_f32 v88, v77, s0
	ds_write_b16 v164, v88 offset:30736
	v_cvt_pk_bf16_f32 v88, v78, s0
	ds_write_b16 v164, v88 offset:31008
	v_cvt_pk_bf16_f32 v88, v79, s0
	ds_write_b16 v164, v88 offset:31280
	s_waitcnt lgkmcnt(0)
	s_barrier
; #define LAS __attribute__((address_space(3)))
; DI float lo16(unsigned u) { return __uint_as_float(u << 16); }
; DI float hi16(unsigned u) { return __uint_as_float(u & 0xffff0000u); }
; DI float silu_fast(float x) { return x * __builtin_amdgcn_rcpf(1.f + __expf(-x)); }
; DI void gdn_seq_phase(const int tid, LAS unsigned char* lds, const P& p, int G, int c) {
;     ...
;             { float o[16]; float ss = 0.f;
; #pragma unroll
;               for (int i = 0; i < 4; ++i) { const f32x4 v = *(const LAS f32x4*)(OT + tt * 132 + e0 + i * 4); o[4 * i] = v[0]; o[4 * i + 1] = v[1]; o[4 * i + 2] = v[2]; o[4 * i + 3] = v[3]; ss += v[0] * v[0] + v[1] * v[1] + v[2] * v[2] + v[3] * v[3]; }
;               ss += __shfl_xor(ss, 1); ss += __shfl_xor(ss, 2); ss += __shfl_xor(ss, 4);
;               const float sc = rsqrtf(ss * (1.f / 128.f) + 1e-6f);
;               float zz[16] = {lo16(z0.x), hi16(z0.x), lo16(z0.y), hi16(z0.y), lo16(z0.z), hi16(z0.z), lo16(z0.w), hi16(z0.w), lo16(z1.x), hi16(z1.x), lo16(z1.y), hi16(z1.y), lo16(z1.z), hi16(z1.z), lo16(z1.w), hi16(z1.w)};
;               float r[16];
; #pragma unroll
;               for (int i = 0; i < 16; ++i) r[i] = o[i] * sc * normw[e0 + i] * silu_fast(zz[i]);
;               u32x4 w0, w1; w0.x = pk2(r[0], r[1]); w0.y = pk2(r[2], r[3]); w0.z = pk2(r[4], r[5]); w0.w = pk2(r[6], r[7]); w1.x = pk2(r[8], r[9]); w1.y = pk2(r[10], r[11]); w1.z = pk2(r[12], r[13]); w1.w = pk2(r[14], r[15]);
;               *(u32x4*)(ycat + tok * 1024 + 256 + h * 128 + e0) = w0; *(u32x4*)(ycat + tok * 1024 + 256 + h * 128 + e0 + 8) = w1; }
	ds_read_b128 v[92:95], v159 offset:53248
	ds_read_b128 v[96:99], v159 offset:53264
	ds_read_b128 v[100:103], v159 offset:53280
	ds_read_b128 v[88:91], v159 offset:53296
	s_brev_b32 s0, 32
	s_waitcnt lgkmcnt(3)
	v_mov_b32_e32 v106, v93
	s_waitcnt lgkmcnt(2)
	v_mov_b32_e32 v107, v97
	v_mov_b32_e32 v104, v92
	v_mov_b32_e32 v105, v96
	v_pk_mul_f32 v[106:107], v[106:107], v[106:107]
	s_waitcnt lgkmcnt(1)
	v_mov_b32_e32 v108, v101
	v_pk_fma_f32 v[104:105], v[104:105], v[104:105], v[106:107]
	v_mov_b32_e32 v106, v94
	v_mov_b32_e32 v107, v98
	v_pk_fma_f32 v[104:105], v[106:107], v[106:107], v[104:105]
	v_mov_b32_e32 v106, v95
	v_mov_b32_e32 v107, v99
	s_waitcnt lgkmcnt(0)
	v_mov_b32_e32 v109, v89
	v_pk_fma_f32 v[104:105], v[106:107], v[106:107], v[104:105]
	v_mov_b32_e32 v106, v100
	v_mov_b32_e32 v107, v88
	v_pk_mul_f32 v[108:109], v[108:109], v[108:109]
	v_add_f32_e32 v104, v104, v105
	v_pk_fma_f32 v[106:107], v[106:107], v[106:107], v[108:109]
	v_mov_b32_e32 v108, v102
	v_mov_b32_e32 v109, v90
	v_pk_fma_f32 v[106:107], v[108:109], v[108:109], v[106:107]
	v_mov_b32_e32 v108, v103
	v_mov_b32_e32 v109, v91
	v_pk_fma_f32 v[106:107], v[108:109], v[108:109], v[106:107]
	s_nop 0
	v_add_f32_e32 v104, v104, v106
	v_add_f32_e32 v104, v104, v107
	ds_bpermute_b32 v105, v160, v104
	s_waitcnt lgkmcnt(0)
	v_add_f32_e32 v104, v104, v105
	ds_bpermute_b32 v105, v161, v104
	s_waitcnt lgkmcnt(0)
	v_add_f32_e32 v104, v104, v105
	ds_bpermute_b32 v105, v162, v104
	s_waitcnt lgkmcnt(0)
	v_add_f32_e32 v104, v104, v105
	v_mov_b32_e32 v105, 0x358637bd
	v_fmamk_f32 v104, v104, 0x3c000000, v105
	v_cmp_gt_f32_e32 vcc, s3, v104
	v_mul_f32_e32 v105, 0x4b800000, v104
	s_nop 0
	v_cndmask_b32_e32 v104, v104, v105, vcc
	v_rsq_f32_e32 v104, v104
	s_nop 0
	v_mul_f32_e32 v105, 0x45800000, v104
	v_cndmask_b32_e32 v172, v104, v105, vcc
	v_pk_mul_f32 v[92:93], v[92:93], v[172:173] op_sel_hi:[1,0]
	v_pk_mul_f32 v[94:95], v[94:95], v[172:173] op_sel_hi:[1,0]
	v_pk_mul_f32 v[96:97], v[96:97], v[172:173] op_sel_hi:[1,0]
	v_pk_mul_f32 v[88:89], v[88:89], v[172:173] op_sel_hi:[1,0]
	v_pk_mul_f32 v[90:91], v[90:91], v[172:173] op_sel_hi:[1,0]
	v_pk_mul_f32 v[88:89], v[184:185], v[88:89]
	v_pk_mul_f32 v[90:91], v[90:91], v[186:187]
	v_pk_mul_f32 v[96:97], v[192:193], v[96:97]
	v_pk_mul_f32 v[92:93], v[196:197], v[92:93]
	v_pk_mul_f32 v[116:117], v[176:177], v[174:175]
	v_pk_mul_f32 v[94:95], v[198:199], v[94:95]
	v_pk_mul_f32 v[92:93], v[116:117], v[92:93]
	s_nop 0
	v_cvt_pk_bf16_f32 v84, v92, v93
	v_lshlrev_b32_e32 v92, 16, v85
	v_and_b32_e32 v93, 0xffff0000, v85
	v_mul_f32_e32 v85, 0xbfb8aa3b, v92
	v_exp_f32_e32 v85, v85
	s_nop 0
	v_add_f32_e32 v85, 1.0, v85
	v_rcp_f32_e32 v116, v85
	v_mul_f32_e32 v85, 0xbfb8aa3b, v93
	v_exp_f32_e32 v85, v85
	s_nop 0
	v_add_f32_e32 v85, 1.0, v85
	v_rcp_f32_e32 v117, v85
	s_nop 0
	v_pk_mul_f32 v[92:93], v[116:117], v[92:93]
	s_nop 0
	v_pk_mul_f32 v[92:93], v[92:93], v[94:95]
	s_nop 0
	v_cvt_pk_bf16_f32 v85, v92, v93
	v_lshlrev_b32_e32 v92, 16, v86
	v_and_b32_e32 v93, 0xffff0000, v86
	v_mul_f32_e32 v86, 0xbfb8aa3b, v92
	v_exp_f32_e32 v86, v86
	s_nop 0
	v_add_f32_e32 v86, 1.0, v86
	v_rcp_f32_e32 v94, v86
	v_mul_f32_e32 v86, 0xbfb8aa3b, v93
	v_exp_f32_e32 v86, v86
	s_nop 0
	v_add_f32_e32 v86, 1.0, v86
	v_rcp_f32_e32 v95, v86
	s_nop 0
	v_pk_mul_f32 v[92:93], v[94:95], v[92:93]
	s_nop 0
	v_pk_mul_f32 v[92:93], v[92:93], v[96:97]
	v_pk_mul_f32 v[96:97], v[98:99], v[172:173] op_sel_hi:[1,0]
	v_cvt_pk_bf16_f32 v86, v92, v93
	v_lshlrev_b32_e32 v92, 16, v87
	v_and_b32_e32 v93, 0xffff0000, v87
	v_mul_f32_e32 v87, 0xbfb8aa3b, v92
	v_exp_f32_e32 v87, v87
	v_pk_mul_f32 v[96:97], v[194:195], v[96:97]
	v_add_f32_e32 v87, 1.0, v87
	v_rcp_f32_e32 v94, v87
	v_mul_f32_e32 v87, 0xbfb8aa3b, v93
	v_exp_f32_e32 v87, v87
	s_nop 0
	v_add_f32_e32 v87, 1.0, v87
	v_rcp_f32_e32 v95, v87
	s_nop 0
	v_pk_mul_f32 v[92:93], v[94:95], v[92:93]
	s_nop 0
	v_pk_mul_f32 v[92:93], v[92:93], v[96:97]
	v_pk_mul_f32 v[96:97], v[100:101], v[172:173] op_sel_hi:[1,0]
	v_cvt_pk_bf16_f32 v87, v92, v93
	s_waitcnt vmcnt(17)
	v_lshlrev_b32_e32 v92, 16, v80
	v_and_b32_e32 v93, 0xffff0000, v80
	v_mul_f32_e32 v80, 0xbfb8aa3b, v92
	v_exp_f32_e32 v80, v80
	v_pk_mul_f32 v[96:97], v[188:189], v[96:97]
	v_add_f32_e32 v80, 1.0, v80
	v_rcp_f32_e32 v94, v80
	v_mul_f32_e32 v80, 0xbfb8aa3b, v93
	v_exp_f32_e32 v80, v80
	s_nop 0
	v_add_f32_e32 v80, 1.0, v80
	v_rcp_f32_e32 v95, v80
	s_nop 0
	v_pk_mul_f32 v[92:93], v[94:95], v[92:93]
	s_nop 0
	v_pk_mul_f32 v[92:93], v[92:93], v[96:97]
	v_pk_mul_f32 v[96:97], v[102:103], v[172:173] op_sel_hi:[1,0]
	v_cvt_pk_bf16_f32 v80, v92, v93
	v_lshlrev_b32_e32 v92, 16, v81
	v_and_b32_e32 v93, 0xffff0000, v81
	v_mul_f32_e32 v81, 0xbfb8aa3b, v92
	v_exp_f32_e32 v81, v81
	v_pk_mul_f32 v[96:97], v[190:191], v[96:97]
	v_add_f32_e32 v81, 1.0, v81
	v_rcp_f32_e32 v94, v81
	v_mul_f32_e32 v81, 0xbfb8aa3b, v93
	v_exp_f32_e32 v81, v81
	s_nop 0
	v_add_f32_e32 v81, 1.0, v81
	v_rcp_f32_e32 v95, v81
	s_nop 0
	v_pk_mul_f32 v[92:93], v[94:95], v[92:93]
	s_nop 0
	v_pk_mul_f32 v[92:93], v[92:93], v[96:97]
	s_nop 0
	v_cvt_pk_bf16_f32 v81, v92, v93
	v_lshlrev_b32_e32 v92, 16, v82
	v_and_b32_e32 v93, 0xffff0000, v82
	v_mul_f32_e32 v82, 0xbfb8aa3b, v92
	v_exp_f32_e32 v82, v82
	s_nop 0
	v_add_f32_e32 v82, 1.0, v82
	v_rcp_f32_e32 v94, v82
	v_mul_f32_e32 v82, 0xbfb8aa3b, v93
	v_exp_f32_e32 v82, v82
	s_nop 0
	v_add_f32_e32 v82, 1.0, v82
	v_rcp_f32_e32 v95, v82
	s_nop 0
	v_pk_mul_f32 v[92:93], v[94:95], v[92:93]
	s_nop 0
	v_pk_mul_f32 v[88:89], v[92:93], v[88:89]
	s_nop 0
	v_cvt_pk_bf16_f32 v82, v88, v89
	v_lshlrev_b32_e32 v88, 16, v83
	v_and_b32_e32 v89, 0xffff0000, v83
	v_mul_f32_e32 v83, 0xbfb8aa3b, v88
	v_exp_f32_e32 v83, v83
	s_nop 0
	v_add_f32_e32 v83, 1.0, v83
	v_rcp_f32_e32 v92, v83
	v_mul_f32_e32 v83, 0xbfb8aa3b, v89
	v_exp_f32_e32 v83, v83
	s_nop 0
	v_add_f32_e32 v83, 1.0, v83
	v_rcp_f32_e32 v93, v83
	s_nop 0
	v_pk_mul_f32 v[88:89], v[92:93], v[88:89]
	s_nop 0
	v_pk_mul_f32 v[88:89], v[88:89], v[90:91]
	s_nop 0
	v_cvt_pk_bf16_f32 v83, v88, v89
	v_lshl_add_u64 v[88:89], v[146:147], 0, s[10:11]
	v_add_co_u32_e32 v88, vcc, s0, v88
	s_mov_b64 s[0:1], 0x20000
	v_lshl_add_u64 v[146:147], v[146:147], 0, s[0:1]
	s_mov_b64 s[0:1], 0x18000
	v_addc_co_u32_e32 v89, vcc, 0, v89, vcc
	v_lshl_add_u64 v[150:151], v[150:151], 0, s[0:1]
	global_store_dwordx4 v[88:89], v[84:87], off offset:512
	global_store_dwordx4 v[88:89], v[80:83], off offset:528
	s_cbranch_scc0 .LBB0_564
	s_waitcnt vmcnt(0)
	v_readlane_b32 s0, v253, 16
	s_add_i32 s8, s8, s0
	s_add_u32 s6, s6, s18
	s_addc_u32 s7, s7, s19
	s_cmpk_gt_i32 s8, 0xbf
	s_barrier
	v_readlane_b32 s1, v253, 17
	s_cbranch_scc0 .LBB0_560
